# phase 3 sample delta item: the seven serialised per-row 2-byte loads of the conv4+silu step (load, full wait, use, repeated) are issued together with row 0; uses take them with v_mov
# speedup vs baseline: 1.0076x; 1.0030x over previous
.LBB0_532:
	s_or_b64 exec, exec, s[2:3]
	s_lshl_b32 s63, s59, 7
	v_readlane_b32 s80, v237, 19
	v_or_b32_e32 v12, s63, v150
	v_readlane_b32 s81, v237, 20
	v_readlane_b32 s82, v237, 21
	v_readlane_b32 s83, v237, 22
	v_readlane_b32 s92, v237, 31
	v_readlane_b32 s93, v237, 32
	v_lshlrev_b32_e32 v4, 2, v12
	v_readlane_b32 s94, v237, 33
	v_readlane_b32 s95, v237, 34
	s_mov_b64 s[80:81], s[92:93]
	v_lshl_add_u64 v[2:3], s[80:81], 0, v[4:5]
	v_add_co_u32_e32 v8, vcc, 0x1000, v2
	s_waitcnt lgkmcnt(0)
	s_nop 0
	v_addc_co_u32_e32 v9, vcc, 0, v3, vcc
	s_barrier
	global_load_dword v7, v[8:9], off offset:2048
	v_add_co_u32_e32 v8, vcc, 0x3000, v2
	v_readlane_b32 s84, v237, 23
	s_nop 0
	v_addc_co_u32_e32 v9, vcc, 0, v3, vcc
	v_add_co_u32_e32 v2, vcc, s69, v2
	v_readlane_b32 s85, v237, 24
	v_readlane_b32 s86, v237, 25
	v_readlane_b32 s87, v237, 26
	v_readlane_b32 s88, v237, 27
	v_readlane_b32 s89, v237, 28
	v_readlane_b32 s90, v237, 29
	v_readlane_b32 s91, v237, 30
	s_mov_b64 s[82:83], s[94:95]
	v_addc_co_u32_e32 v3, vcc, 0, v3, vcc
	global_load_dword v6, v4, s[80:81]
	s_mul_i32 s2, s76, 3
	global_load_dword v8, v[8:9], off
	s_movk_i32 s3, 0x3000
	global_load_dword v9, v[2:3], off offset:2048
	v_readlane_b32 s80, v237, 3
	v_readlane_b32 s86, v237, 9
	v_readlane_b32 s87, v237, 10
	v_add_u32_e32 v47, 64, v200
	v_readlane_b32 s81, v237, 4
	v_lshl_add_u64 v[2:3], s[86:87], 0, v[4:5]
	v_mad_i64_i32 v[2:3], s[54:55], s2, v208, v[2:3]
	v_add_co_u32_e32 v10, vcc, s73, v2
	global_load_dword v13, v[2:3], off
	s_nop 0
	v_addc_co_u32_e32 v11, vcc, 0, v3, vcc
	global_load_dword v14, v[10:11], off offset:2048
	v_add_co_u32_e32 v2, vcc, s3, v2
	s_mul_hi_i32 s3, s58, 0x1c00
	s_mulk_i32 s58, 0x1c00
	v_readlane_b32 s54, v236, 3
	v_readlane_b32 s55, v236, 4
	s_add_u32 s54, s54, s58
	v_addc_co_u32_e32 v3, vcc, 0, v3, vcc
	s_addc_u32 s55, s55, s3
	v_lshlrev_b32_e32 v4, 1, v12
	global_load_dword v15, v[2:3], off
	v_lshl_add_u64 v[2:3], s[54:55], 0, v[4:5]
	v_add_u32_e32 v28, 0x1c00, v4
	global_load_ushort v20, v28, s[54:55] offset:3072
	v_add_u32_e32 v28, 0x1c00, v28
	global_load_ushort v21, v28, s[54:55] offset:3072
	v_add_u32_e32 v28, 0x1c00, v28
	global_load_ushort v22, v28, s[54:55] offset:3072
	v_add_u32_e32 v28, 0x1c00, v28
	global_load_ushort v23, v28, s[54:55] offset:3072
	v_add_u32_e32 v28, 0x1c00, v28
	global_load_ushort v24, v28, s[54:55] offset:3072
	v_add_u32_e32 v28, 0x1c00, v28
	global_load_ushort v25, v28, s[54:55] offset:3072
	v_add_u32_e32 v28, 0x1c00, v28
	global_load_ushort v26, v28, s[54:55] offset:3072
	global_load_ushort v4, v4, s[54:55] offset:3072
	s_movk_i32 s3, 0x2000
	v_readlane_b32 s82, v237, 5
	v_readlane_b32 s83, v237, 6
	v_readlane_b32 s84, v237, 7
	v_readlane_b32 s85, v237, 8
	v_readlane_b32 s88, v237, 11
	v_readlane_b32 s89, v237, 12
	v_readlane_b32 s90, v237, 13
	v_readlane_b32 s91, v237, 14
	v_readlane_b32 s92, v237, 15
	v_readlane_b32 s93, v237, 16
	v_readlane_b32 s94, v237, 17
	v_readlane_b32 s95, v237, 18
	s_waitcnt vmcnt(9)
	v_mul_f32_e32 v10, v7, v14
	v_fmac_f32_e32 v10, v6, v13
	s_waitcnt vmcnt(8)
	v_fmac_f32_e32 v10, v8, v15
	s_waitcnt vmcnt(0)
	v_lshlrev_b32_e32 v4, 16, v4
	v_fmac_f32_e32 v10, v9, v4
	v_mul_f32_e32 v11, 0xbfb8aa3b, v10
	v_exp_f32_e32 v11, v11
	s_nop 0
	v_add_f32_e32 v11, 1.0, v11
	v_rcp_f32_e32 v11, v11
	s_nop 0
	v_mul_f32_e32 v10, v10, v11
	v_cvt_pk_bf16_f32 v10, v10, s0
	ds_write_b16 v151, v10
	v_add_co_u32_e32 v10, vcc, s3, v2
	s_movk_i32 s3, 0x6000
	s_nop 0
	v_addc_co_u32_e32 v11, vcc, 0, v3, vcc
	v_mov_b32_e32 v10, v20
	s_waitcnt vmcnt(0)
	v_lshlrev_b32_e32 v12, 16, v10
	v_mul_f32_e32 v10, v7, v15
	v_fmac_f32_e32 v10, v6, v14
	v_fmac_f32_e32 v10, v8, v4
	v_fmac_f32_e32 v10, v9, v12
	v_mul_f32_e32 v11, 0xbfb8aa3b, v10
	v_exp_f32_e32 v11, v11
	s_nop 0
	v_add_f32_e32 v11, 1.0, v11
	v_rcp_f32_e32 v11, v11
	s_nop 0
	v_mul_f32_e32 v10, v10, v11
	v_cvt_pk_bf16_f32 v10, v10, s0
	ds_write_b16 v151, v10 offset:272
	v_add_co_u32_e32 v10, vcc, s69, v2
	s_nop 1
	v_addc_co_u32_e32 v11, vcc, 0, v3, vcc
	v_mov_b32_e32 v10, v21
	s_waitcnt vmcnt(0)
	v_lshlrev_b32_e32 v13, 16, v10
	v_mul_f32_e32 v10, v7, v4
	v_fmac_f32_e32 v10, v6, v15
	v_fmac_f32_e32 v10, v8, v12
	v_fmac_f32_e32 v10, v9, v13
	v_mul_f32_e32 v11, 0xbfb8aa3b, v10
	v_exp_f32_e32 v11, v11
	s_nop 0
	v_add_f32_e32 v11, 1.0, v11
	v_rcp_f32_e32 v11, v11
	s_nop 0
	v_mul_f32_e32 v10, v10, v11
	v_cvt_pk_bf16_f32 v10, v10, s0
	ds_write_b16 v151, v10 offset:544
	v_add_co_u32_e32 v10, vcc, s3, v2
	s_movk_i32 s3, 0x7000
	s_nop 0
	v_addc_co_u32_e32 v11, vcc, 0, v3, vcc
	v_mov_b32_e32 v10, v22
	s_waitcnt vmcnt(0)
	v_lshlrev_b32_e32 v14, 16, v10
	v_mul_f32_e32 v10, v7, v12
	v_fmac_f32_e32 v10, v6, v4
	v_fmac_f32_e32 v10, v8, v13
	v_fmac_f32_e32 v10, v9, v14
	v_mul_f32_e32 v4, 0xbfb8aa3b, v10
	v_exp_f32_e32 v4, v4
	s_nop 0
	v_add_f32_e32 v4, 1.0, v4
	v_rcp_f32_e32 v4, v4
	s_nop 0
	v_mul_f32_e32 v4, v10, v4
	v_add_co_u32_e32 v10, vcc, s3, v2
	v_cvt_pk_bf16_f32 v4, v4, s0
	s_nop 0
	v_addc_co_u32_e32 v11, vcc, 0, v3, vcc
	ds_write_b16 v151, v4 offset:816
	v_mov_b32_e32 v4, v23
	v_mul_f32_e32 v10, v7, v13
	v_fmac_f32_e32 v10, v6, v12
	v_fmac_f32_e32 v10, v8, v14
	s_mov_b32 s3, 0x9000
	s_waitcnt vmcnt(0)
	v_lshlrev_b32_e32 v4, 16, v4
	v_fmac_f32_e32 v10, v9, v4
	v_mul_f32_e32 v11, 0xbfb8aa3b, v10
	v_exp_f32_e32 v11, v11
	s_nop 0
	v_add_f32_e32 v11, 1.0, v11
	v_rcp_f32_e32 v11, v11
	s_nop 0
	v_mul_f32_e32 v10, v10, v11
	v_cvt_pk_bf16_f32 v10, v10, s0
	ds_write_b16 v151, v10 offset:1088
	v_add_co_u32_e32 v10, vcc, s3, v2
	s_mov_b32 s3, 0xb000
	s_nop 0
	v_addc_co_u32_e32 v11, vcc, 0, v3, vcc
	v_mov_b32_e32 v10, v24
	s_waitcnt vmcnt(0)
	v_lshlrev_b32_e32 v12, 16, v10
	v_mul_f32_e32 v10, v7, v14
	v_fmac_f32_e32 v10, v6, v13
	v_fmac_f32_e32 v10, v8, v4
	v_fmac_f32_e32 v10, v9, v12
	v_mul_f32_e32 v11, 0xbfb8aa3b, v10
	v_exp_f32_e32 v11, v11
	s_nop 0
	v_add_f32_e32 v11, 1.0, v11
	v_rcp_f32_e32 v11, v11
	s_nop 0
	v_mul_f32_e32 v10, v10, v11
	v_cvt_pk_bf16_f32 v10, v10, s0
	ds_write_b16 v151, v10 offset:1360
	v_add_co_u32_e32 v10, vcc, s3, v2
	s_mov_b32 s3, 0xd000
	s_nop 0
	v_addc_co_u32_e32 v11, vcc, 0, v3, vcc
	v_add_co_u32_e32 v2, vcc, s3, v2
	v_mov_b32_e32 v10, v25
	s_nop 0
	v_addc_co_u32_e32 v3, vcc, 0, v3, vcc
	v_mov_b32_e32 v2, v26
	v_mul_f32_e32 v11, v7, v4
	v_mul_f32_e32 v3, v7, v12
	v_fmac_f32_e32 v11, v6, v14
	v_fmac_f32_e32 v3, v6, v4
	v_fmac_f32_e32 v11, v8, v12
	s_waitcnt vmcnt(1)
	v_lshlrev_b32_e32 v10, 16, v10
	v_fmac_f32_e32 v3, v8, v10
	v_fmac_f32_e32 v11, v9, v10
	s_waitcnt vmcnt(0)
	v_lshlrev_b32_e32 v2, 16, v2
	v_fmac_f32_e32 v3, v9, v2
	v_mul_f32_e32 v13, 0xbfb8aa3b, v11
	v_mul_f32_e32 v2, 0xbfb8aa3b, v3
	v_exp_f32_e32 v13, v13
	v_exp_f32_e32 v2, v2
	v_add_f32_e32 v13, 1.0, v13
	v_add_f32_e32 v2, 1.0, v2
	v_rcp_f32_e32 v13, v13
	v_rcp_f32_e32 v2, v2
	v_mul_f32_e32 v11, v11, v13
	v_mul_f32_e32 v2, v3, v2
	v_cvt_pk_bf16_f32 v11, v11, s0
	v_cvt_pk_bf16_f32 v2, v2, s0
	ds_write_b16 v151, v11 offset:1632
	ds_write_b16 v151, v2 offset:1904
	ds_write_b16 v151, v5 offset:2176
	ds_write_b16 v151, v5 offset:2448
	ds_write_b16 v151, v5 offset:2720
	ds_write_b16 v151, v5 offset:2992
	ds_write_b16 v151, v5 offset:3264
	ds_write_b16 v151, v5 offset:3536
	ds_write_b16 v151, v5 offset:3808
	ds_write_b16 v151, v5 offset:4080
	ds_write_b16 v151, v5 offset:4352
	ds_write_b16 v151, v5 offset:4624
	ds_write_b16 v151, v5 offset:4896
	ds_write_b16 v151, v5 offset:5168
	ds_write_b16 v151, v5 offset:5440
	ds_write_b16 v151, v5 offset:5712
	ds_write_b16 v151, v5 offset:5984
	ds_write_b16 v151, v5 offset:6256
	ds_write_b16 v151, v5 offset:6528
	ds_write_b16 v151, v5 offset:6800
	ds_write_b16 v151, v5 offset:7072
	ds_write_b16 v151, v5 offset:7344
	ds_write_b16 v151, v5 offset:7616
	ds_write_b16 v151, v5 offset:7888
	ds_write_b16 v151, v5 offset:8160
	ds_write_b16 v151, v5 offset:8432
	ds_write_b16 v151, v5 offset:8704
	ds_write_b16 v151, v5 offset:8976
	ds_write_b16 v151, v5 offset:9248
	ds_write_b16 v151, v5 offset:9520
	ds_write_b16 v151, v5 offset:9792
	ds_write_b16 v151, v5 offset:10064
	ds_write_b16 v151, v5 offset:10336
	ds_write_b16 v151, v5 offset:10608
	ds_write_b16 v151, v5 offset:10880
	ds_write_b16 v151, v5 offset:11152
	ds_write_b16 v151, v5 offset:11424
	ds_write_b16 v151, v5 offset:11696
	ds_write_b16 v151, v5 offset:11968
	ds_write_b16 v151, v5 offset:12240
	ds_write_b16 v151, v5 offset:12512
	ds_write_b16 v151, v5 offset:12784
	ds_write_b16 v151, v5 offset:13056
	ds_write_b16 v151, v5 offset:13328
	ds_write_b16 v151, v5 offset:13600
	ds_write_b16 v151, v5 offset:13872
	ds_write_b16 v151, v5 offset:14144
	ds_write_b16 v151, v5 offset:14416
	ds_write_b16 v151, v5 offset:14688
	ds_write_b16 v151, v5 offset:14960
	ds_write_b16 v151, v5 offset:15232
	ds_write_b16 v151, v5 offset:15504
	ds_write_b16 v151, v5 offset:15776
	ds_write_b16 v151, v5 offset:16048
	ds_write_b16 v151, v5 offset:16320
	ds_write_b16 v151, v5 offset:16592
	ds_write_b16 v151, v5 offset:16864
	ds_write_b16 v151, v5 offset:17136
	s_waitcnt lgkmcnt(0)
	s_barrier
	ds_read2_b64 v[12:15], v153 offset1:4
	ds_read2_b64 v[18:21], v219 offset0:128 offset1:132
	ds_read2_b64 v[28:31], v153 offset0:8 offset1:12
	ds_read2_b64 v[34:37], v219 offset0:136 offset1:140
	ds_read2_b64 v[50:53], v153 offset0:16 offset1:20
	ds_read2_b64 v[56:59], v219 offset0:144 offset1:148
	ds_read2_b64 v[66:69], v153 offset0:24 offset1:28
	ds_read2_b64 v[70:73], v219 offset0:152 offset1:156
	s_waitcnt lgkmcnt(7)
	v_lshlrev_b32_e32 v2, 16, v12
	v_and_b32_e32 v3, 0xffff0000, v12
	v_lshlrev_b32_e32 v6, 16, v13
	v_and_b32_e32 v7, 0xffff0000, v13
	v_pk_mul_f32 v[76:77], v[2:3], v[2:3]
	v_pk_mul_f32 v[80:81], v[6:7], v[6:7]
	v_add_f32_e32 v45, v76, v77
	s_waitcnt lgkmcnt(6)
	v_lshlrev_b32_e32 v8, 16, v18
	v_and_b32_e32 v9, 0xffff0000, v18
	v_lshlrev_b32_e32 v12, 16, v14
	v_and_b32_e32 v13, 0xffff0000, v14
	v_add_f32_e32 v45, v45, v80
	v_lshlrev_b32_e32 v10, 16, v19
	v_and_b32_e32 v11, 0xffff0000, v19
	v_pk_mul_f32 v[74:75], v[8:9], v[8:9]
	v_pk_mul_f32 v[84:85], v[12:13], v[12:13]
	v_add_f32_e32 v45, v81, v45
	v_lshlrev_b32_e32 v14, 16, v15
	v_and_b32_e32 v15, 0xffff0000, v15
	v_pk_mul_f32 v[78:79], v[10:11], v[10:11]
	v_add_f32_e32 v4, v74, v75
	v_add_f32_e32 v45, v45, v84
	v_lshlrev_b32_e32 v18, 16, v20
	v_and_b32_e32 v19, 0xffff0000, v20
	v_pk_mul_f32 v[88:89], v[14:15], v[14:15]
	v_add_f32_e32 v4, v4, v78
	v_add_f32_e32 v45, v85, v45
	v_lshlrev_b32_e32 v16, 16, v21
	v_and_b32_e32 v17, 0xffff0000, v21
	s_waitcnt lgkmcnt(5)
	v_lshlrev_b32_e32 v20, 16, v28
	v_and_b32_e32 v21, 0xffff0000, v28
	v_pk_mul_f32 v[82:83], v[18:19], v[18:19]
	v_add_f32_e32 v4, v79, v4
	v_add_f32_e32 v45, v88, v45
	v_pk_mul_f32 v[92:93], v[20:21], v[20:21]
	v_add_f32_e32 v4, v4, v82
	v_add_f32_e32 v45, v89, v45
	v_lshlrev_b32_e32 v22, 16, v29
	v_and_b32_e32 v23, 0xffff0000, v29
	v_pk_mul_f32 v[86:87], v[16:17], v[16:17]
	v_add_f32_e32 v4, v83, v4
	v_add_f32_e32 v45, v45, v92
	s_waitcnt lgkmcnt(4)
	v_lshlrev_b32_e32 v24, 16, v34
	v_and_b32_e32 v25, 0xffff0000, v34
	v_pk_mul_f32 v[96:97], v[22:23], v[22:23]
	v_add_f32_e32 v4, v86, v4
	v_add_f32_e32 v45, v93, v45
	v_lshlrev_b32_e32 v28, 16, v30
	v_and_b32_e32 v29, 0xffff0000, v30
	v_pk_mul_f32 v[90:91], v[24:25], v[24:25]
	v_add_f32_e32 v4, v87, v4
	v_add_f32_e32 v45, v96, v45
	v_lshlrev_b32_e32 v26, 16, v35
	v_and_b32_e32 v27, 0xffff0000, v35
	v_pk_mul_f32 v[100:101], v[28:29], v[28:29]
	v_add_f32_e32 v4, v4, v90
	v_add_f32_e32 v45, v97, v45
	v_lshlrev_b32_e32 v30, 16, v31
	v_and_b32_e32 v31, 0xffff0000, v31
	v_pk_mul_f32 v[94:95], v[26:27], v[26:27]
	v_add_f32_e32 v4, v91, v4
	v_add_f32_e32 v45, v45, v100
	v_lshlrev_b32_e32 v34, 16, v36
	v_and_b32_e32 v35, 0xffff0000, v36
	v_pk_mul_f32 v[104:105], v[30:31], v[30:31]
	v_add_f32_e32 v4, v94, v4
	v_add_f32_e32 v45, v101, v45
	v_lshlrev_b32_e32 v32, 16, v37
	v_and_b32_e32 v33, 0xffff0000, v37
	s_waitcnt lgkmcnt(3)
	v_lshlrev_b32_e32 v36, 16, v50
	v_and_b32_e32 v37, 0xffff0000, v50
	v_pk_mul_f32 v[98:99], v[34:35], v[34:35]
	v_add_f32_e32 v4, v95, v4
	v_add_f32_e32 v45, v104, v45
	v_pk_mul_f32 v[108:109], v[36:37], v[36:37]
	v_add_f32_e32 v4, v4, v98
	v_add_f32_e32 v45, v105, v45
	v_lshlrev_b32_e32 v38, 16, v51
	v_and_b32_e32 v39, 0xffff0000, v51
	v_pk_mul_f32 v[102:103], v[32:33], v[32:33]
	v_add_f32_e32 v4, v99, v4
	v_add_f32_e32 v45, v45, v108
	s_waitcnt lgkmcnt(2)
	v_lshlrev_b32_e32 v40, 16, v56
	v_and_b32_e32 v41, 0xffff0000, v56
	v_pk_mul_f32 v[112:113], v[38:39], v[38:39]
	v_add_f32_e32 v4, v102, v4
	v_add_f32_e32 v45, v109, v45
	v_lshlrev_b32_e32 v50, 16, v52
	v_and_b32_e32 v51, 0xffff0000, v52
	v_pk_mul_f32 v[106:107], v[40:41], v[40:41]
	v_add_f32_e32 v4, v103, v4
	v_add_f32_e32 v45, v112, v45
	v_lshlrev_b32_e32 v48, 16, v57
	v_and_b32_e32 v49, 0xffff0000, v57
	v_pk_mul_f32 v[116:117], v[50:51], v[50:51]
	v_add_f32_e32 v4, v4, v106
	v_add_f32_e32 v45, v113, v45
	v_lshlrev_b32_e32 v52, 16, v53
	v_and_b32_e32 v53, 0xffff0000, v53
	v_pk_mul_f32 v[110:111], v[48:49], v[48:49]
	v_add_f32_e32 v4, v107, v4
	v_add_f32_e32 v45, v45, v116
	v_lshlrev_b32_e32 v56, 16, v58
	v_and_b32_e32 v57, 0xffff0000, v58
	v_pk_mul_f32 v[120:121], v[52:53], v[52:53]
	v_add_f32_e32 v4, v110, v4
	v_add_f32_e32 v45, v117, v45
	v_lshlrev_b32_e32 v54, 16, v59
	v_and_b32_e32 v55, 0xffff0000, v59
	s_waitcnt lgkmcnt(1)
	v_lshlrev_b32_e32 v58, 16, v66
	v_and_b32_e32 v59, 0xffff0000, v66
	v_pk_mul_f32 v[114:115], v[56:57], v[56:57]
	v_add_f32_e32 v4, v111, v4
	v_add_f32_e32 v45, v120, v45
	v_pk_mul_f32 v[124:125], v[58:59], v[58:59]
	v_add_f32_e32 v4, v4, v114
	v_add_f32_e32 v45, v121, v45
	v_lshlrev_b32_e32 v60, 16, v67
	v_and_b32_e32 v61, 0xffff0000, v67
	v_pk_mul_f32 v[118:119], v[54:55], v[54:55]
	v_add_f32_e32 v4, v115, v4
	v_add_f32_e32 v45, v45, v124
	s_waitcnt lgkmcnt(0)
	v_lshlrev_b32_e32 v62, 16, v70
	v_and_b32_e32 v63, 0xffff0000, v70
	v_pk_mul_f32 v[128:129], v[60:61], v[60:61]
	v_add_f32_e32 v4, v118, v4
	v_add_f32_e32 v45, v125, v45
	v_lshlrev_b32_e32 v66, 16, v68
	v_and_b32_e32 v67, 0xffff0000, v68
	v_pk_mul_f32 v[122:123], v[62:63], v[62:63]
	v_add_f32_e32 v4, v119, v4
	v_add_f32_e32 v45, v128, v45
	v_lshlrev_b32_e32 v64, 16, v71
	v_and_b32_e32 v65, 0xffff0000, v71
	v_pk_mul_f32 v[132:133], v[66:67], v[66:67]
	v_add_f32_e32 v4, v4, v122
	v_add_f32_e32 v45, v129, v45
	v_lshlrev_b32_e32 v68, 16, v69
	v_and_b32_e32 v69, 0xffff0000, v69
	v_pk_mul_f32 v[126:127], v[64:65], v[64:65]
	v_add_f32_e32 v4, v123, v4
	v_add_f32_e32 v45, v45, v132
	v_lshlrev_b32_e32 v70, 16, v72
	v_and_b32_e32 v71, 0xffff0000, v72
	v_pk_mul_f32 v[136:137], v[68:69], v[68:69]
	v_add_f32_e32 v4, v126, v4
	v_add_f32_e32 v45, v133, v45
	v_pk_mul_f32 v[130:131], v[70:71], v[70:71]
	v_add_f32_e32 v4, v127, v4
	v_add_f32_e32 v45, v136, v45
	v_lshlrev_b32_e32 v72, 16, v73
	v_and_b32_e32 v73, 0xffff0000, v73
	v_add_f32_e32 v4, v4, v130
	v_add_f32_e32 v74, v137, v45
	v_xor_b32_e32 v45, 16, v199
	v_pk_mul_f32 v[134:135], v[72:73], v[72:73]
	v_add_f32_e32 v4, v131, v4
	v_cmp_lt_i32_e32 vcc, v45, v47
	v_add_f32_e32 v4, v134, v4
	v_add_f32_e32 v4, v135, v4
	v_cndmask_b32_e32 v45, v199, v45, vcc
	v_lshlrev_b32_e32 v75, 2, v45
	ds_bpermute_b32 v45, v75, v4
	ds_bpermute_b32 v75, v75, v74
	s_waitcnt lgkmcnt(1)
	v_add_f32_e32 v45, v4, v45
	v_xor_b32_e32 v4, 32, v199
	v_cmp_lt_i32_e32 vcc, v4, v47
	s_waitcnt lgkmcnt(0)
	v_add_f32_e32 v74, v74, v75
	v_cndmask_b32_e32 v4, v199, v4, vcc
	v_lshlrev_b32_e32 v4, 2, v4
	ds_bpermute_b32 v47, v4, v45
	ds_bpermute_b32 v75, v4, v74
	v_mov_b32_e32 v4, 0
	s_and_saveexec_b64 s[56:57], s[22:23]
	s_cbranch_execz .LBB0_534
	s_waitcnt lgkmcnt(1)
	v_add_f32_e32 v4, v45, v47
	v_add_f32_e32 v4, 0x358637bd, v4
	v_mul_f32_e32 v45, 0x4b800000, v4
	v_cmp_gt_f32_e32 vcc, s75, v4
	s_nop 1
	v_cndmask_b32_e32 v4, v4, v45, vcc
	v_rsq_f32_e32 v4, v4
	s_nop 0
	v_mul_f32_e32 v45, 0x45800000, v4
	v_cndmask_b32_e32 v4, v4, v45, vcc
	v_mul_f32_e32 v4, 0x3db504f3, v4
